# MLA: static s_setprio 1 for waves 4-7 during the attention phase, on top of the interleave fast path
# baseline (speedup 1.0000x reference)
; DI unsigned pack2(float a, float b) { bf2_t v = __builtin_convertvector((f32x2){a, b}, bf2_t); return __builtin_bit_cast(unsigned, v); }
; template <int DQK, int MODE, bool QN, bool KN> ...
;     ...
;   float inv = 1.f;
;   if (MODE != 2) { const float lt = l_run + __shfl_xor(l_run, 32); inv = 1.f / lt; }
; #pragma unroll
;   for (int dvb = 0; dvb < 2; ++dvb)
; #pragma unroll
;     for (int g = 0; g < 4; ++g) {
;       u32x2 w;
;       w.x = pack2(o[dvb][4 * g] * inv, o[dvb][4 * g + 1] * inv); w.y = pack2(o[dvb][4 * g + 2] * inv, o[dvb][4 * g + 3] * inv);
;       *(u32x2*)(O + (size_t)(wave * 32 + r) * DM + dvb * 32 + 8 * g + 4 * h) = w;
;     }
;   __syncthreads();
; template <int LAYER>
; DI void attn_phase(const Params& p, char* smem) {
;   char* ws = p.ws;
;   bf16_t* mix = (bf16_t*)(ws + O_MIX);
;   const int xcd = (int)(blockIdx.x & 7), lb = (int)(blockIdx.x >> 3), L = (int)(gridDim.x >> 3);
;   for (int j = lb; j < 192 + 64; j += L) {
;     if (j < 192) {
;       const int hl = j >> 4, qi = j & 15, qt = ((j / L) & 1) ? (15 - qi) : qi, bh = hl * 8 + xcd, b = bh / 12, hd = bh % 12, q0 = qt * 256;
;       const size_t tok0 = (size_t)b * SEQ;
;       bf16_t* O = mix + (tok0 + q0) * DM + hd * 64;
;       if (LAYER == 0) {
;         const bf16_t* P = (const bf16_t*)(ws + O_P);
;         attn_item<64, 2, false, false>(P + (tok0 + q0) * 2560 + hd * 64, 2560, P + tok0 * 2560 + 768 + hd * 64, 2560, P + tok0 * 2560 + 1536 + hd * 64, 2560,
;                                        q0, q0 / 64 + 4, O, 0.125f, smem, nullptr, 1.f, nullptr, nullptr);
;       } else {
;         const bf16_t* Qb = (const bf16_t*)(ws + O_QB);
;         const bf16_t* Kn = (const bf16_t*)(ws + O_KN);
;         const bf16_t* V1 = (const bf16_t*)(ws + O_V1);
;         attn_item<96, 1, true, false>(Qb + (tok0 + q0) * 1152 + hd * 96, 1152, Kn + tok0 * 1152 + hd * 96, 1152, V1 + tok0 * 768 + hd * 64, 768,
;                                       q0, q0 / 64 + 4, O, 1.f, smem, p.mla_g_qn, 0.14724138410008716f, p.pos + tok0 + q0, p.mla_g_kn);
.LBB0_1164:
	s_or_b64 exec, exec, s[0:1]
	v_readlane_b32 s0, v254, 25
	v_readlane_b32 s1, v254, 26
	s_andn2_b64 vcc, exec, s[0:1]
	s_waitcnt lgkmcnt(0)
	s_barrier
	s_cbranch_vccnz .LBB0_1237
	s_lshl_b32 s9, s52, 12
	s_lshl_b32 s0, s52, 18
	s_add_u32 s0, s86, s0
	s_addc_u32 s1, s87, 0
	v_mbcnt_hi_u32_b32 v226, -1, v213
	s_add_u32 s24, s0, 0xb7a0000
	s_mov_b32 s0, 0x11000
	v_and_b32_e32 v0, 64, v226
	s_mov_b32 s7, 0
	s_addc_u32 s25, s1, 0
	s_movk_i32 s26, 0xb00
	s_movk_i32 s27, 0xffe0
	v_mov_b32_e32 v1, 0
	s_mov_b32 s8, 0x3c800000
	s_mov_b32 s28, 0x800000
	v_mov_b32_e32 v215, 0x3c23d70a
	s_mov_b32 s29, 0x42400000
	s_mov_b32 s30, 0x20000
	s_movk_i32 s31, 0x90
	s_movk_i32 s34, 0x110
	s_mov_b32 s35, 0xff800000
	s_movk_i32 s36, 0x900
	s_movk_i32 s37, 0x600
	s_mov_b32 s38, 0xc2fc0000
	v_mov_b32_e32 v214, 0x358637bd
	s_mov_b32 s39, 0x2aaaaaab
	s_movk_i32 s40, 0xd0
	s_add_i32 s41, s0, 0x110
	v_xor_b32_e32 v227, 32, v226
	v_add_u32_e32 v228, 64, v0
	v_xor_b32_e32 v229, 1, v226
	v_xor_b32_e32 v230, 2, v226
	v_xor_b32_e32 v231, 4, v226
	v_mov_b32_e32 v232, 0x42800000
	v_not_b32_e32 v233, 63
	v_mov_b32_e32 v234, 0xff800000
	v_readfirstlane_b32 s101, v212
	s_nop 3
	s_lshr_b32 s101, s101, 8
	s_cmp_lg_u32 s101, 0
	s_cbranch_scc0 .Lprio_skip
	s_setprio 1
.Lprio_skip:
	s_branch .LBB0_1168
.LBB0_1166:
	v_mov_b64_e32 v[32:33], v[128:129]
	v_mov_b64_e32 v[34:35], v[130:131]
	v_mov_b64_e32 v[36:37], v[132:133]
	v_mov_b64_e32 v[38:39], v[134:135]
	v_mov_b64_e32 v[40:41], v[136:137]
	v_mov_b64_e32 v[42:43], v[138:139]
	v_mov_b64_e32 v[44:45], v[140:141]
	v_mov_b64_e32 v[46:47], v[142:143]
	v_mov_b64_e32 v[48:49], v[96:97]
	v_mov_b64_e32 v[50:51], v[98:99]
	v_mov_b64_e32 v[52:53], v[100:101]
	v_mov_b64_e32 v[54:55], v[102:103]
	v_mov_b64_e32 v[56:57], v[104:105]
	v_mov_b64_e32 v[58:59], v[106:107]
	v_mov_b64_e32 v[60:61], v[108:109]
	v_mov_b64_e32 v[62:63], v[110:111]
	ds_bpermute_b32 v0, v235, v253
	s_lshl_b64 s[0:1], s[6:7], 11
	v_readlane_b32 s2, v254, 23
	s_add_u32 s2, s2, s0
	v_readlane_b32 s0, v254, 24
	s_waitcnt lgkmcnt(0)
	v_add_f32_e32 v0, v253, v0
	s_addc_u32 s3, s0, s1
	v_div_scale_f32 v2, s[0:1], v0, v0, 1.0
	v_rcp_f32_e32 v3, v2
	s_lshl_b32 s0, s44, 1
	s_add_u32 s0, s2, s0
	s_addc_u32 s1, s3, 0
	v_fma_f32 v4, -v2, v3, 1.0
	v_fmac_f32_e32 v3, v4, v3
	v_div_scale_f32 v4, vcc, 1.0, v0, 1.0
	v_mul_f32_e32 v5, v4, v3
	v_fma_f32 v6, -v2, v5, v4
	v_fmac_f32_e32 v5, v6, v3
	v_fma_f32 v2, -v2, v5, v4
	v_div_fmas_f32 v2, v2, v3, v5
	v_div_fixup_f32 v2, v2, v0, 1.0
	v_lshlrev_b64 v[4:5], 11, v[216:217]
	v_lshl_add_u64 v[4:5], s[0:1], 0, v[4:5]
	v_lshlrev_b32_e32 v0, 1, v247
	v_pk_mul_f32 v[6:7], v[48:49], v[2:3] op_sel_hi:[1,0]
	v_pk_mul_f32 v[8:9], v[50:51], v[2:3] op_sel_hi:[1,0]
	v_lshl_add_u64 v[4:5], v[4:5], 0, v[0:1]
	v_cvt_pk_bf16_f32 v6, v6, v7
	v_cvt_pk_bf16_f32 v7, v8, v9
	global_store_dwordx2 v[4:5], v[6:7], off
	v_pk_mul_f32 v[6:7], v[52:53], v[2:3] op_sel_hi:[1,0]
	v_pk_mul_f32 v[8:9], v[54:55], v[2:3] op_sel_hi:[1,0]
	v_cvt_pk_bf16_f32 v6, v6, v7
	v_cvt_pk_bf16_f32 v7, v8, v9
	global_store_dwordx2 v[4:5], v[6:7], off offset:16
	v_pk_mul_f32 v[6:7], v[56:57], v[2:3] op_sel_hi:[1,0]
	v_pk_mul_f32 v[8:9], v[58:59], v[2:3] op_sel_hi:[1,0]
	v_cvt_pk_bf16_f32 v6, v6, v7
	v_cvt_pk_bf16_f32 v7, v8, v9
	global_store_dwordx2 v[4:5], v[6:7], off offset:32
	v_pk_mul_f32 v[6:7], v[60:61], v[2:3] op_sel_hi:[1,0]
	v_pk_mul_f32 v[8:9], v[62:63], v[2:3] op_sel_hi:[1,0]
	v_cvt_pk_bf16_f32 v6, v6, v7
	v_cvt_pk_bf16_f32 v7, v8, v9
	global_store_dwordx2 v[4:5], v[6:7], off offset:48
	v_pk_mul_f32 v[6:7], v[32:33], v[2:3] op_sel_hi:[1,0]
	v_pk_mul_f32 v[8:9], v[34:35], v[2:3] op_sel_hi:[1,0]
	v_cvt_pk_bf16_f32 v6, v6, v7
	v_cvt_pk_bf16_f32 v7, v8, v9
	global_store_dwordx2 v[4:5], v[6:7], off offset:64
	v_pk_mul_f32 v[6:7], v[36:37], v[2:3] op_sel_hi:[1,0]
	v_pk_mul_f32 v[8:9], v[38:39], v[2:3] op_sel_hi:[1,0]
	v_cvt_pk_bf16_f32 v6, v6, v7
	v_cvt_pk_bf16_f32 v7, v8, v9
	global_store_dwordx2 v[4:5], v[6:7], off offset:80
	v_pk_mul_f32 v[6:7], v[40:41], v[2:3] op_sel_hi:[1,0]
	v_pk_mul_f32 v[8:9], v[42:43], v[2:3] op_sel_hi:[1,0]
	v_cvt_pk_bf16_f32 v6, v6, v7
	v_cvt_pk_bf16_f32 v7, v8, v9
	global_store_dwordx2 v[4:5], v[6:7], off offset:96
	v_pk_mul_f32 v[6:7], v[44:45], v[2:3] op_sel_hi:[1,0]
	v_pk_mul_f32 v[2:3], v[46:47], v[2:3] op_sel_hi:[1,0]
	v_cvt_pk_bf16_f32 v6, v6, v7
	v_cvt_pk_bf16_f32 v7, v2, v3
	global_store_dwordx2 v[4:5], v[6:7], off offset:112
	s_barrier
